# diff-attn unit prologue placement padding moved into unreachable code (same layout, no executed nops)
# speedup vs baseline: 1.0154x; 1.0154x over previous
.LBB0_288:
	s_or_b64 exec, exec, s[0:1]
	v_readlane_b32 s0, v253, 11
	v_mov_b32_e32 v156, v173
	v_readlane_b32 s1, v253, 12
	s_waitcnt lgkmcnt(0)
	s_barrier
	s_andn2_b64 vcc, exec, s[0:1]
	v_readfirstlane_b32 s2, v156
	s_cbranch_vccnz .LBB0_346
	s_and_b32 s0, s64, 2
	s_lshl_b32 s0, s0, 2
	v_mov_b32_e32 v0, s0
	v_readlane_b32 s0, v253, 7
	v_readlane_b32 s1, v253, 8
	s_lshl_b32 s90, s68, 7
	v_readlane_b32 s3, v253, 9
	s_mov_b32 s20, s30
	s_nop 1
	global_load_dwordx2 v[144:145], v0, s[0:1]
	s_lshl_b64 s[0:1], s[90:91], 2
	s_add_u32 s0, s3, s0
	v_readlane_b32 s3, v253, 10
	s_addc_u32 s1, s3, s1
	s_ashr_i32 s4, s2, 6
	s_ashr_i32 s3, s2, 8
	s_lshl_b32 s5, s4, 12
	s_add_i32 s16, s5, 0
	s_lshl_b32 s4, s4, 5
	s_lshl_b32 s6, s3, 6
	s_add_i32 s16, s16, 0x1a200
	s_and_b32 s17, s4, 0x60
	s_ashr_i32 s7, s6, 31
	s_cmp_eq_u32 s3, 1
	s_cselect_b64 s[8:9], -1, 0
	s_cmpk_lt_u32 s2, 0x100
	s_mul_i32 s18, s3, 0x2400
	s_cselect_b64 s[10:11], -1, 0
	s_or_b32 s19, s17, 0xffffff81
	s_branch .LBB0_291
	s_nop 0
	s_nop 0
	s_nop 0
	s_nop 0
	s_nop 0
	s_nop 0
	s_nop 0
	s_nop 0
	s_nop 0
	s_nop 0
	s_nop 0
	s_nop 0
	s_nop 0
	s_nop 0
	s_nop 0
	s_nop 0
	s_nop 0
	s_nop 0
	s_nop 0
	s_nop 0
	s_nop 0
	s_nop 0
	s_nop 0
	s_nop 0
	s_nop 0
	s_nop 0
	s_nop 0
	s_nop 0
	s_nop 0
	s_nop 0
	s_nop 0
	s_nop 0
	s_nop 0
	s_nop 0
	s_nop 0
	s_nop 0
	s_nop 0
	s_nop 0
	s_nop 0
	s_nop 0
	s_nop 0
	s_nop 0
	s_nop 0
	s_nop 0
	s_nop 0
	s_nop 0
	s_nop 0
	s_nop 0
	s_nop 0
	s_nop 0
	s_nop 0
	s_nop 0
	s_nop 0
	s_nop 0
	s_nop 0
	s_nop 0
	s_nop 0
	s_nop 0

.LBB0_301:
	s_or_b64 exec, exec, s[2:3]
	s_ashr_i32 s12, s14, 3
	s_ashr_i32 s13, s12, 31
	s_lshl_b64 s[2:3], s[12:13], 13
	s_lshl_b32 s13, s22, 7
	v_and_b32_e32 v4, 31, v159
	s_ashr_i32 s4, s13, 31
	v_and_b32_e32 v0, 63, v159
	s_add_u32 s5, s2, s13
	v_or_b32_e32 v158, s17, v4
	v_lshlrev_b32_e32 v0, 4, v0
	v_or_b32_e32 v146, s5, v158
	v_mov_b64_e32 v[6:7], s[48:49]
	v_add_u32_e32 v162, s16, v0
	s_addc_u32 s14, s3, s4
	v_mad_u64_u32 v[0:1], s[4:5], v146, s53, v[6:7]
	v_mad_i32_i24 v1, s14, v216, v1
	s_lshl_b32 s90, s21, 8
	v_bfe_u32 v5, v159, 5, 1
	v_lshl_add_u64 v[0:1], v[0:1], 0, s[90:91]
	v_lshl_add_u64 v[0:1], s[6:7], 1, v[0:1]
	v_lshlrev_b32_e32 v168, 4, v5
	v_lshl_add_u64 v[8:9], v[0:1], 0, v[168:169]
	global_load_dwordx4 v[112:115], v[8:9], off
	global_load_dwordx4 v[116:119], v[8:9], off offset:32
	global_load_dwordx4 v[120:123], v[8:9], off offset:64
	global_load_dwordx4 v[124:127], v[8:9], off offset:96
	v_ashrrev_i32_e32 v128, 3, v159
	v_ashrrev_i32_e32 v129, 31, v128
	v_ashrrev_i32_e32 v130, 4, v159
	v_mov_b32_e32 v23, v169
	v_ashrrev_i32_e32 v131, 31, v130
	s_or_b32 s23, s13, s17
	v_lshlrev_b32_e32 v157, 2, v5
	v_or_b32_e32 v5, s23, v4
	s_cmpk_gt_i32 s23, 0x627
	v_mov_b32_e32 v147, s14
	v_lshlrev_b32_e32 v8, 4, v159
	v_and_b32_e32 v22, 0x70, v8
	v_lshl_add_u64 v[0:1], s[2:3], 0, v[128:129]
	v_mad_u64_u32 v[2:3], s[4:5], v0, s53, v[6:7]
	v_mad_i32_i24 v3, v1, s53, v3
	v_lshl_add_u64 v[0:1], v[2:3], 0, s[90:91]
	v_lshl_add_u64 v[2:3], v[0:1], 0, v[22:23]
	v_lshl_add_u64 v[0:1], s[2:3], 0, v[130:131]
	v_mad_u64_u32 v[6:7], s[2:3], v0, s53, v[6:7]
	v_mad_i32_i24 v7, v1, s53, v7
	s_movk_i32 s2, 0x90
	v_lshl_add_u64 v[0:1], v[6:7], 0, s[90:91]
	v_and_b32_e32 v6, 0xf0, v8
	v_mov_b32_e32 v7, v169
	v_mul_lo_u32 v23, v128, s2
	s_movk_i32 s2, 0x140
	v_mad_u64_u32 v[132:133], s[2:3], v130, s2, v[6:7]
	v_lshl_add_u64 v[0:1], v[0:1], 0, v[6:7]
	s_movk_i32 s2, 0x1000
	v_add_co_u32_e32 v14, vcc, s2, v0
	s_mov_b32 s2, 0x31000
	s_nop 0
	v_addc_co_u32_e32 v15, vcc, 0, v1, vcc
	global_load_dwordx4 v[6:9], v[2:3], off offset:2048
	global_load_dwordx4 v[10:13], v[2:3], off offset:2176
	v_add_co_u32_e32 v18, vcc, s2, v0
	global_load_dwordx4 v[14:17], v[14:15], off
	s_nop 0
	v_addc_co_u32_e32 v19, vcc, 0, v1, vcc
	global_load_dwordx4 v[18:21], v[18:19], off
	v_add_co_u32_e32 v56, vcc, 0x60000, v2
	s_nop 1
	v_addc_co_u32_e32 v57, vcc, 0, v3, vcc
	global_load_dwordx4 v[48:51], v[56:57], off offset:2048
	global_load_dwordx4 v[52:55], v[56:57], off offset:2176
	v_add3_u32 v163, v23, v22, 0
	s_mov_b32 s2, 0x60000
	v_add_u32_e32 v164, 0, v132
	s_cselect_b64 s[4:5], -1, 0
	s_cmpk_lt_i32 s23, 0x628
	v_sub_u32_e32 v129, v5, v157
	s_waitcnt vmcnt(10)
	ds_write_b128 v228, v[220:223]
	s_mov_b64 s[62:63], exec
	v_cmpx_gt_i32_e32 vcc, 32, v159
	s_nop 1
	ds_write_b128 v228, v[224:227] offset:8192
	s_mov_b64 exec, s[62:63]
	s_waitcnt vmcnt(6)
	ds_write_b128 v162, v[112:115]
	ds_write_b128 v162, v[116:119] offset:1024
	ds_write_b128 v162, v[120:123] offset:2048
	ds_write_b128 v162, v[124:127] offset:3072
	s_waitcnt vmcnt(5)
	ds_write_b128 v163, v[6:9]
	s_waitcnt vmcnt(4)
	ds_write_b128 v163, v[10:13] offset:9216
	s_waitcnt vmcnt(3)
	ds_write_b128 v164, v[14:17] offset:36864
	s_waitcnt vmcnt(2)
	ds_write_b128 v164, v[18:21] offset:47104
	v_readlane_b32 s2, v254, 57
	s_waitcnt vmcnt(1)
	ds_write_b128 v163, v[48:51] offset:18432
	s_waitcnt vmcnt(0)
	ds_write_b128 v163, v[52:55] offset:27648
	v_mov_b32_e32 v6, s2
	s_waitcnt lgkmcnt(0)
	s_barrier
	ds_read_b32 v165, v6
	s_mov_b64 s[2:3], -1
	s_cbranch_scc0 .LBB0_303
	s_add_i32 s2, 0, 0x18000
	v_lshl_add_u32 v5, v129, 2, s2
	ds_read2_b32 v[6:7], v5 offset0:127 offset1:128
	ds_read2_b32 v[8:9], v5 offset0:125 offset1:126
	ds_read2_b32 v[10:11], v5 offset0:119 offset1:120
	ds_read2_b32 v[12:13], v5 offset0:117 offset1:118
	ds_read2_b32 v[14:15], v5 offset0:95 offset1:96
	ds_read2_b32 v[32:33], v5 offset0:93 offset1:94
	ds_read2_b32 v[34:35], v5 offset0:87 offset1:88
	ds_read2_b32 v[36:37], v5 offset0:85 offset1:86
	ds_read2_b32 v[16:17], v5 offset0:111 offset1:112
	ds_read2_b32 v[18:19], v5 offset0:109 offset1:110
	ds_read2_b32 v[20:21], v5 offset0:103 offset1:104
	ds_read2_b32 v[22:23], v5 offset0:101 offset1:102
	ds_read2_b32 v[38:39], v5 offset0:79 offset1:80
	ds_read2_b32 v[40:41], v5 offset0:77 offset1:78
	ds_read2_b32 v[42:43], v5 offset0:71 offset1:72
	ds_read2_b32 v[56:57], v5 offset0:69 offset1:70
	s_mov_b64 s[2:3], 0
	s_waitcnt lgkmcnt(4)
	v_mov_b32_e32 v31, v22
	v_mov_b32_e32 v30, v23
	v_mov_b32_e32 v29, v20
	v_mov_b32_e32 v28, v21
	v_mov_b32_e32 v27, v18
	v_mov_b32_e32 v26, v19
	v_mov_b32_e32 v25, v16
	v_mov_b32_e32 v24, v17
	v_mov_b32_e32 v23, v12
	v_mov_b32_e32 v22, v13
	v_mov_b32_e32 v21, v10
	v_mov_b32_e32 v20, v11
	v_mov_b32_e32 v19, v8
	v_mov_b32_e32 v18, v9
	v_mov_b32_e32 v17, v6
	v_mov_b32_e32 v16, v7
	s_waitcnt lgkmcnt(0)
	v_mov_b32_e32 v46, v57
	v_mov_b32_e32 v45, v42
	v_mov_b32_e32 v44, v43
	v_mov_b32_e32 v43, v40
	v_mov_b32_e32 v42, v41
	v_mov_b32_e32 v41, v38
	v_mov_b32_e32 v40, v39
	v_mov_b32_e32 v39, v36
	v_mov_b32_e32 v38, v37
	v_mov_b32_e32 v37, v34
	v_mov_b32_e32 v36, v35
	v_mov_b32_e32 v35, v32
	v_mov_b32_e32 v34, v33
	v_mov_b32_e32 v33, v14
	v_mov_b32_e32 v32, v15
	v_mov_b32_e32 v47, v56
